# attention output epilogue: lane^1 exchange by DPP quad_perm instead of ds_bpermute (64 LDS round trips per block removed), on top of v065
# speedup vs baseline: 1.0075x; 1.0009x over previous
; #define FOX_GETC() ({ unsigned r_ = xb_add(qhead + 128, 1u); if (r_ < NC) r_ += NA; else { r_ = xb_add(qhead + 64, 1u); r_ = r_ < NA ? (unsigned)NITEMS - 1u - r_ : (unsigned)NITEMS; } r_; })
; #define FOX_GETA() ({ unsigned r_ = xb_add(qhead, 1u); if (r_ >= NA) r_ = FOX_GETC(); r_; })
; #define FOX_GETB() ({ unsigned r_ = xb_add(qhead + 64, 1u); r_ = r_ < NA ? (unsigned)NITEMS - 1u - r_ : FOX_GETC(); r_; })
; __global__ void __launch_bounds__(NWAVES * 64, 2) mk_fwd(Args args) {
;     ...
;         { float mq = fmaxf(fabsf(fox_qn[lane]), fabsf(fox_qn[64 + lane])), mk = fmaxf(fabsf(fox_kn[lane]), fabsf(fox_kn[64 + lane]));
; #pragma unroll
;           for (int o = 1; o < 64; o <<= 1) { mq = fmaxf(mq, __shfl_xor(mq, o)); mk = fmaxf(mk, __shfl_xor(mk, o)); }
;           const float Bq = 11.3137085f * 1.02f * mq * mk;
;           skipT = __builtin_bit_cast(float, __builtin_amdgcn_readfirstlane(__builtin_bit_cast(int, 11.3137085f * (92.9f + 2.0f * Bq + 3.0f)))); }
;         constexpr int NITEMS = BATCH * NH * (SEQ / fox::QB);
;         unsigned* qhead = ctl + CW_QUEUE;
;         constexpr unsigned NA = 192, NC = (unsigned)NITEMS - 2 * NA;
;     ...
;         const unsigned* QORD = (const unsigned*)(ws + WS_EG + 65536);
;     ...
;         if (tid == 0) { if (bx < BATCH * NH) { MISC[12] = FOX_GETC(); MISC[13] = FOX_GETC(); } else { MISC[12] = FOX_GETA(); MISC[13] = FOX_GETB(); } }
.LBB0_553:
	s_nop 0
	v_lshlrev_b64 v[2:3], 2, v[198:199]
	v_lshl_add_u64 v[4:5], s[80:81], 0, v[2:3]
	global_load_dword v6, v[4:5], off
	s_nop 0
	global_load_dword v4, v[4:5], off offset:256
	v_lshl_add_u64 v[2:3], s[82:83], 0, v[2:3]
	global_load_dword v5, v[2:3], off offset:256
	s_nop 0
	global_load_dword v2, v[2:3], off
	v_mbcnt_lo_u32_b32 v1, -1, 0
	v_mbcnt_hi_u32_b32 v3, -1, v1
	v_and_b32_e32 v1, 64, v3
	v_xor_b32_e32 v7, 1, v3
	v_add_u32_e32 v13, 64, v1
	v_cmp_lt_i32_e32 vcc, v7, v13
	v_xor_b32_e32 v8, 2, v3
	v_xor_b32_e32 v9, 4, v3
	v_cndmask_b32_e32 v1, v3, v7, vcc
	v_lshlrev_b32_e32 v1, 2, v1
	v_cmp_lt_i32_e32 vcc, v8, v13
	v_xor_b32_e32 v10, 8, v3
	v_xor_b32_e32 v11, 16, v3
	v_cndmask_b32_e32 v7, v3, v8, vcc
	v_lshlrev_b32_e32 v7, 2, v7
	v_cmp_lt_i32_e32 vcc, v9, v13
	v_xor_b32_e32 v12, 32, v3
	v_cmp_eq_u32_e64 s[0:1], 0, v0
	s_waitcnt vmcnt(0)
	v_max_f32_e64 v6, |v6|, |v6|
	v_max_f32_e64 v4, |v4|, |v4|
	v_max_f32_e64 v5, |v5|, |v5|
	v_max_f32_e64 v2, |v2|, |v2|
	v_max_f32_e32 v4, v6, v4
	v_max_f32_e32 v2, v2, v5
	s_nop 1
	v_mov_b32_dpp v5, v4 quad_perm:[1,0,3,2] row_mask:0xf bank_mask:0xf
	s_nop 1
	v_mov_b32_dpp v6, v2 quad_perm:[1,0,3,2] row_mask:0xf bank_mask:0xf
	s_waitcnt lgkmcnt(1)
	v_max_f32_e32 v5, v5, v5
	s_waitcnt lgkmcnt(0)
	v_max_f32_e32 v6, v6, v6
	v_max_f32_e32 v4, v4, v5
	v_max_f32_e32 v2, v2, v6
	ds_bpermute_b32 v5, v7, v4
	ds_bpermute_b32 v6, v7, v2
	v_cndmask_b32_e32 v7, v3, v9, vcc
	v_lshlrev_b32_e32 v7, 2, v7
	v_cmp_lt_i32_e32 vcc, v10, v13
	s_waitcnt lgkmcnt(1)
	v_max_f32_e32 v5, v5, v5
	s_waitcnt lgkmcnt(0)
	v_max_f32_e32 v6, v6, v6
	v_max_f32_e32 v4, v4, v5
	v_max_f32_e32 v2, v2, v6
	ds_bpermute_b32 v5, v7, v4
	ds_bpermute_b32 v6, v7, v2
	v_cndmask_b32_e32 v7, v3, v10, vcc
	v_lshlrev_b32_e32 v7, 2, v7
	v_cmp_lt_i32_e32 vcc, v11, v13
	s_waitcnt lgkmcnt(1)
	v_max_f32_e32 v5, v5, v5
	s_waitcnt lgkmcnt(0)
	v_max_f32_e32 v6, v6, v6
	v_max_f32_e32 v4, v4, v5
	v_max_f32_e32 v2, v2, v6
	ds_bpermute_b32 v5, v7, v4
	ds_bpermute_b32 v6, v7, v2
	v_cndmask_b32_e32 v7, v3, v11, vcc
	v_lshlrev_b32_e32 v7, 2, v7
	v_cmp_lt_i32_e32 vcc, v12, v13
	s_waitcnt lgkmcnt(1)
	v_max_f32_e32 v5, v5, v5
	s_waitcnt lgkmcnt(0)
	v_max_f32_e32 v6, v6, v6
	v_max_f32_e32 v4, v4, v5
	v_max_f32_e32 v2, v2, v6
	ds_bpermute_b32 v5, v7, v4
	ds_bpermute_b32 v6, v7, v2
	v_cndmask_b32_e32 v3, v3, v12, vcc
	v_lshlrev_b32_e32 v3, 2, v3
	s_waitcnt lgkmcnt(1)
	v_max_f32_e32 v5, v5, v5
	s_waitcnt lgkmcnt(0)
	v_max_f32_e32 v6, v6, v6
	v_max_f32_e32 v4, v4, v5
	v_max_f32_e32 v2, v2, v6
	ds_bpermute_b32 v5, v3, v4
	ds_bpermute_b32 v3, v3, v2
	s_waitcnt lgkmcnt(1)
	v_max_f32_e32 v5, v5, v5
	s_waitcnt lgkmcnt(0)
	v_max_f32_e32 v3, v3, v3
	v_max_f32_e32 v4, v4, v5
	v_max_f32_e32 v2, v2, v3
	v_mul_f32_e32 v3, 0x4138a3c4, v4
	v_mul_f32_e32 v2, v2, v3
	s_nop 0
	v_readfirstlane_b32 s24, v2
	s_and_saveexec_b64 s[4:5], s[0:1]
	s_cbranch_execz .LBB0_601
	s_and_b64 vcc, exec, s[6:7]
	s_cbranch_vccz .LBB0_582
	s_mov_b64 s[8:9], exec
	v_mbcnt_lo_u32_b32 v2, s8, 0
	v_mbcnt_hi_u32_b32 v2, s9, v2
	v_cmp_eq_u32_e32 vcc, 0, v2
	s_and_saveexec_b64 s[6:7], vcc
	s_cbranch_execz .LBB0_557
	s_bcnt1_i32_b64 s8, s[8:9]
	v_mov_b32_e32 v3, 0x8000
	v_mov_b32_e32 v4, s8
	global_atomic_add v3, v3, v4, s[64:65] sc0

; #define SBAR() __builtin_amdgcn_sched_barrier(0)
; __device__ __forceinline__ int crow(int r, int hi) { return (r & 3) + 8 * (r >> 2) + 4 * hi; }
; __device__ __forceinline__ unsigned cvtpk(float lo, float hi) { unsigned r; asm volatile("v_cvt_pk_bf16_f32 %0, %1, %2" : "=v"(r) : "v"(lo), "v"(hi)); return r; }
; #define SEAM_K0() do { VMWN(NQL); SWRITE_HK(0); SBAR(); } while (0)
;     static __device__ __forceinline__ void block(const BlockRef& cur, const BlockRef& nxt, int skv, char* lds, Seam& S) {
;     ...
;         SBAR(); SEAM_K0();
;         if (hi == 0) li_l[r32] = l_reg; asm volatile("s_waitcnt lgkmcnt(0)" ::: "memory");
;         float rli[16];
; #pragma unroll
;         for (int r = 0; r < 16; ++r) rli[r] = __builtin_amdgcn_rcpf(li_l[crow(r, hi)]);
;         bf16* Ow = cur.O + (unsigned)((wid * QBLK) * LDO);
; #pragma unroll
;         for (int r = 0; r < 16; ++r) { const int orow = crow(r, hi);
; #pragma unroll
;             for (int d0 = 0; d0 < 4; ++d0) { const float v = o[d0][r] * rli[r];
;                 const float vn = __shfl_xor(v, 1);
;                 if ((r32 & 1) == 0) *(unsigned*)(Ow + (unsigned)(orow * LDO + d0 * 32 + r32)) = cvtpk(v, vn); } }
.LBB0_648:
	s_waitcnt vmcnt(8)
	s_waitcnt vmcnt(10)
	ds_write_b128 v226, v[118:121] offset:32768
	s_waitcnt vmcnt(8)
	ds_write_b128 v226, v[126:129] offset:40960
	s_and_saveexec_b64 s[8:9], s[4:5]
	ds_write_b32 v230, v2
	s_or_b64 exec, exec, s[8:9]
	s_waitcnt lgkmcnt(0)
	ds_read_b128 v[82:85], v229
	ds_read_b128 v[12:15], v229 offset:32
	ds_read_b128 v[8:11], v229 offset:64
	ds_read_b128 v[4:7], v229 offset:96
	s_lshl_b32 s8, s62, 12
	s_add_u32 s8, s36, s8
	s_waitcnt lgkmcnt(3)
	v_rcp_f32_e32 v16, v82
	s_addc_u32 s9, s37, 0
	v_lshlrev_b32_e32 v2, 1, v202
	v_mul_f32_e32 v17, v66, v16
	s_nop 1
	v_mov_b32_dpp v66, v17 quad_perm:[1,0,3,2] row_mask:0xf bank_mask:0xf
	s_and_saveexec_b64 s[10:11], s[6:7]
	s_cbranch_execz .LBB0_652
	s_waitcnt lgkmcnt(0)
	v_cvt_pk_bf16_f32 v17, v17, v66
	global_store_dword v2, v17, s[8:9]
.LBB0_652:
	s_or_b64 exec, exec, s[10:11]
	v_mul_f32_e32 v17, v50, v16
	s_nop 1
	v_mov_b32_dpp v50, v17 quad_perm:[1,0,3,2] row_mask:0xf bank_mask:0xf
	s_and_saveexec_b64 s[10:11], s[6:7]
	s_cbranch_execz .LBB0_654
	s_waitcnt lgkmcnt(0)
	v_cvt_pk_bf16_f32 v17, v17, v50
	global_store_dword v2, v17, s[8:9] offset:64
.LBB0_654:
	s_or_b64 exec, exec, s[10:11]
	v_mul_f32_e32 v17, v34, v16
	s_nop 1
	v_mov_b32_dpp v34, v17 quad_perm:[1,0,3,2] row_mask:0xf bank_mask:0xf
	s_and_saveexec_b64 s[10:11], s[6:7]
	s_cbranch_execz .LBB0_656
	s_waitcnt lgkmcnt(0)
	v_cvt_pk_bf16_f32 v17, v17, v34
	global_store_dword v2, v17, s[8:9] offset:128
.LBB0_656:
	s_or_b64 exec, exec, s[10:11]
	v_mul_f32_e32 v16, v18, v16
	s_nop 1
	v_mov_b32_dpp v17, v16 quad_perm:[1,0,3,2] row_mask:0xf bank_mask:0xf
	s_and_saveexec_b64 s[10:11], s[6:7]
	s_cbranch_execz .LBB0_658
	s_waitcnt lgkmcnt(0)
	v_cvt_pk_bf16_f32 v16, v16, v17
	global_store_dword v2, v16, s[8:9] offset:192
.LBB0_658:
	s_or_b64 exec, exec, s[10:11]
	v_rcp_f32_e32 v16, v83
	s_waitcnt lgkmcnt(0)
	v_mul_f32_e32 v17, v67, v16
	s_nop 1
	v_mov_b32_dpp v18, v17 quad_perm:[1,0,3,2] row_mask:0xf bank_mask:0xf
	s_and_saveexec_b64 s[10:11], s[6:7]
	s_cbranch_execz .LBB0_660
	v_lshl_add_u64 v[66:67], s[8:9], 0, v[2:3]
	v_add_co_u32_e32 v66, vcc, 0x1000, v66
	s_waitcnt lgkmcnt(0)
	v_cvt_pk_bf16_f32 v17, v17, v18
	s_nop 0
	v_addc_co_u32_e32 v67, vcc, 0, v67, vcc
	global_store_dword v[66:67], v17, off
.LBB0_660:
	s_or_b64 exec, exec, s[10:11]
	v_mul_f32_e32 v17, v51, v16
	s_waitcnt lgkmcnt(0)
	s_nop 1
	v_mov_b32_dpp v18, v17 quad_perm:[1,0,3,2] row_mask:0xf bank_mask:0xf
	s_and_saveexec_b64 s[10:11], s[6:7]
	s_cbranch_execz .LBB0_662
	v_lshl_add_u64 v[50:51], s[8:9], 0, v[2:3]
	v_add_co_u32_e32 v50, vcc, 0x1000, v50
	s_waitcnt lgkmcnt(0)
	v_cvt_pk_bf16_f32 v17, v17, v18
	s_nop 0
	v_addc_co_u32_e32 v51, vcc, 0, v51, vcc
	global_store_dword v[50:51], v17, off offset:64
.LBB0_662:
	s_or_b64 exec, exec, s[10:11]
	v_mul_f32_e32 v17, v35, v16
	s_waitcnt lgkmcnt(0)
	s_nop 1
	v_mov_b32_dpp v18, v17 quad_perm:[1,0,3,2] row_mask:0xf bank_mask:0xf
	s_and_saveexec_b64 s[10:11], s[6:7]
	s_cbranch_execz .LBB0_664
	v_lshl_add_u64 v[34:35], s[8:9], 0, v[2:3]
	v_add_co_u32_e32 v34, vcc, 0x1000, v34
	s_waitcnt lgkmcnt(0)
	v_cvt_pk_bf16_f32 v17, v17, v18
	s_nop 0
	v_addc_co_u32_e32 v35, vcc, 0, v35, vcc
	global_store_dword v[34:35], v17, off offset:128
.LBB0_664:
	s_or_b64 exec, exec, s[10:11]
	v_mul_f32_e32 v16, v19, v16
	s_nop 1
	v_mov_b32_dpp v17, v16 quad_perm:[1,0,3,2] row_mask:0xf bank_mask:0xf
	s_and_saveexec_b64 s[10:11], s[6:7]
	s_cbranch_execz .LBB0_666
	s_waitcnt lgkmcnt(1)
	v_lshl_add_u64 v[18:19], s[8:9], 0, v[2:3]
	s_waitcnt lgkmcnt(0)
	v_cvt_pk_bf16_f32 v34, v16, v17
	v_add_co_u32_e32 v16, vcc, 0x1000, v18
	s_nop 1
	v_addc_co_u32_e32 v17, vcc, 0, v19, vcc
	global_store_dword v[16:17], v34, off offset:192
.LBB0_666:
	s_or_b64 exec, exec, s[10:11]
	v_rcp_f32_e32 v16, v84
	s_waitcnt lgkmcnt(0)
	v_mul_f32_e32 v17, v68, v16
	s_nop 1
	v_mov_b32_dpp v18, v17 quad_perm:[1,0,3,2] row_mask:0xf bank_mask:0xf
	s_and_saveexec_b64 s[10:11], s[6:7]
	s_cbranch_execz .LBB0_668
	v_lshl_add_u64 v[34:35], s[8:9], 0, v[2:3]
	s_waitcnt lgkmcnt(0)
	v_cvt_pk_bf16_f32 v17, v17, v18
	v_add_co_u32_e32 v18, vcc, 0x2000, v34
	s_nop 1
	v_addc_co_u32_e32 v19, vcc, 0, v35, vcc
	global_store_dword v[18:19], v17, off
.LBB0_668:
	s_or_b64 exec, exec, s[10:11]
	v_mul_f32_e32 v17, v52, v16
	s_waitcnt lgkmcnt(0)
	s_nop 1
	v_mov_b32_dpp v18, v17 quad_perm:[1,0,3,2] row_mask:0xf bank_mask:0xf
	s_and_saveexec_b64 s[10:11], s[6:7]
	s_cbranch_execz .LBB0_670
	v_lshl_add_u64 v[34:35], s[8:9], 0, v[2:3]
	s_waitcnt lgkmcnt(0)
	v_cvt_pk_bf16_f32 v17, v17, v18
	v_add_co_u32_e32 v18, vcc, 0x2000, v34
	s_nop 1
	v_addc_co_u32_e32 v19, vcc, 0, v35, vcc
	global_store_dword v[18:19], v17, off offset:64
.LBB0_670:
	s_or_b64 exec, exec, s[10:11]
	v_mul_f32_e32 v17, v36, v16
	s_waitcnt lgkmcnt(0)
	s_nop 1
	v_mov_b32_dpp v18, v17 quad_perm:[1,0,3,2] row_mask:0xf bank_mask:0xf
	s_and_saveexec_b64 s[10:11], s[6:7]
	s_cbranch_execz .LBB0_672
	v_lshl_add_u64 v[34:35], s[8:9], 0, v[2:3]
	s_waitcnt lgkmcnt(0)
	v_cvt_pk_bf16_f32 v17, v17, v18
	v_add_co_u32_e32 v18, vcc, 0x2000, v34
	s_nop 1
	v_addc_co_u32_e32 v19, vcc, 0, v35, vcc
	global_store_dword v[18:19], v17, off offset:128
.LBB0_672:
	s_or_b64 exec, exec, s[10:11]
	v_mul_f32_e32 v16, v20, v16
	s_nop 1
	v_mov_b32_dpp v17, v16 quad_perm:[1,0,3,2] row_mask:0xf bank_mask:0xf
	s_and_saveexec_b64 s[10:11], s[6:7]
	s_cbranch_execz .LBB0_674
	s_waitcnt lgkmcnt(1)
	v_lshl_add_u64 v[18:19], s[8:9], 0, v[2:3]
	s_waitcnt lgkmcnt(0)
	v_cvt_pk_bf16_f32 v20, v16, v17
	v_add_co_u32_e32 v16, vcc, 0x2000, v18
	s_nop 1
	v_addc_co_u32_e32 v17, vcc, 0, v19, vcc
	global_store_dword v[16:17], v20, off offset:192
; __device__ __forceinline__ int crow(int r, int hi) { return (r & 3) + 8 * (r >> 2) + 4 * hi; }
; __device__ __forceinline__ unsigned cvtpk(float lo, float hi) { unsigned r; asm volatile("v_cvt_pk_bf16_f32 %0, %1, %2" : "=v"(r) : "v"(lo), "v"(hi)); return r; }
;     static __device__ __forceinline__ void block(const BlockRef& cur, const BlockRef& nxt, int skv, char* lds, Seam& S) {
;     ...
;         for (int r = 0; r < 16; ++r) rli[r] = __builtin_amdgcn_rcpf(li_l[crow(r, hi)]);
;         bf16* Ow = cur.O + (unsigned)((wid * QBLK) * LDO);
; #pragma unroll
;         for (int r = 0; r < 16; ++r) { const int orow = crow(r, hi);
; #pragma unroll
;             for (int d0 = 0; d0 < 4; ++d0) { const float v = o[d0][r] * rli[r];
;                 const float vn = __shfl_xor(v, 1);
;                 if ((r32 & 1) == 0) *(unsigned*)(Ow + (unsigned)(orow * LDO + d0 * 32 + r32)) = cvtpk(v, vn); } }
.LBB0_674:
	s_or_b64 exec, exec, s[10:11]
	v_rcp_f32_e32 v16, v85
	s_waitcnt lgkmcnt(0)
	v_mul_f32_e32 v17, v69, v16
	s_nop 1
	v_mov_b32_dpp v18, v17 quad_perm:[1,0,3,2] row_mask:0xf bank_mask:0xf
	s_and_saveexec_b64 s[10:11], s[6:7]
	s_cbranch_execz .LBB0_676
	v_lshl_add_u64 v[34:35], s[8:9], 0, v[2:3]
	s_waitcnt lgkmcnt(0)
	v_cvt_pk_bf16_f32 v17, v17, v18
	v_add_co_u32_e32 v18, vcc, 0x3000, v34
	s_nop 1
	v_addc_co_u32_e32 v19, vcc, 0, v35, vcc
	global_store_dword v[18:19], v17, off
.LBB0_676:
	s_or_b64 exec, exec, s[10:11]
	v_mul_f32_e32 v17, v53, v16
	s_waitcnt lgkmcnt(0)
	s_nop 1
	v_mov_b32_dpp v18, v17 quad_perm:[1,0,3,2] row_mask:0xf bank_mask:0xf
	s_and_saveexec_b64 s[10:11], s[6:7]
	s_cbranch_execz .LBB0_678
	v_lshl_add_u64 v[34:35], s[8:9], 0, v[2:3]
	s_waitcnt lgkmcnt(0)
	v_cvt_pk_bf16_f32 v17, v17, v18
	v_add_co_u32_e32 v18, vcc, 0x3000, v34
	s_nop 1
	v_addc_co_u32_e32 v19, vcc, 0, v35, vcc
	global_store_dword v[18:19], v17, off offset:64
.LBB0_678:
	s_or_b64 exec, exec, s[10:11]
	v_mul_f32_e32 v17, v37, v16
	s_waitcnt lgkmcnt(0)
	s_nop 1
	v_mov_b32_dpp v18, v17 quad_perm:[1,0,3,2] row_mask:0xf bank_mask:0xf
	s_and_saveexec_b64 s[10:11], s[6:7]
	s_cbranch_execz .LBB0_680
	v_lshl_add_u64 v[34:35], s[8:9], 0, v[2:3]
	s_waitcnt lgkmcnt(0)
	v_cvt_pk_bf16_f32 v17, v17, v18
	v_add_co_u32_e32 v18, vcc, 0x3000, v34
	s_nop 1
	v_addc_co_u32_e32 v19, vcc, 0, v35, vcc
	global_store_dword v[18:19], v17, off offset:128
.LBB0_680:
	s_or_b64 exec, exec, s[10:11]
	v_mul_f32_e32 v16, v21, v16
	s_nop 1
	v_mov_b32_dpp v17, v16 quad_perm:[1,0,3,2] row_mask:0xf bank_mask:0xf
	s_and_saveexec_b64 s[10:11], s[6:7]
	s_cbranch_execz .LBB0_682
	s_waitcnt lgkmcnt(1)
	v_lshl_add_u64 v[18:19], s[8:9], 0, v[2:3]
	s_waitcnt lgkmcnt(0)
	v_cvt_pk_bf16_f32 v20, v16, v17
	v_add_co_u32_e32 v16, vcc, 0x3000, v18
	s_nop 1
	v_addc_co_u32_e32 v17, vcc, 0, v19, vcc
	global_store_dword v[16:17], v20, off offset:192
.LBB0_682:
	s_or_b64 exec, exec, s[10:11]
	v_rcp_f32_e32 v12, v12
	s_nop 0
	v_mul_f32_e32 v16, v70, v12
	s_waitcnt lgkmcnt(0)
	s_nop 1
	v_mov_b32_dpp v17, v16 quad_perm:[1,0,3,2] row_mask:0xf bank_mask:0xf
	s_and_saveexec_b64 s[10:11], s[6:7]
	s_cbranch_execz .LBB0_684
	v_lshl_add_u64 v[18:19], s[8:9], 0, v[2:3]
	s_waitcnt lgkmcnt(0)
	v_cvt_pk_bf16_f32 v20, v16, v17
	v_add_co_u32_e32 v16, vcc, 0x8000, v18
	s_nop 1
	v_addc_co_u32_e32 v17, vcc, 0, v19, vcc
	global_store_dword v[16:17], v20, off
.LBB0_684:
	s_or_b64 exec, exec, s[10:11]
	v_mul_f32_e32 v16, v54, v12
	s_waitcnt lgkmcnt(0)
	s_nop 1
	v_mov_b32_dpp v17, v16 quad_perm:[1,0,3,2] row_mask:0xf bank_mask:0xf
	s_and_saveexec_b64 s[10:11], s[6:7]
	s_cbranch_execz .LBB0_686
	v_lshl_add_u64 v[18:19], s[8:9], 0, v[2:3]
	s_waitcnt lgkmcnt(0)
	v_cvt_pk_bf16_f32 v20, v16, v17
	v_add_co_u32_e32 v16, vcc, 0x8000, v18
	s_nop 1
	v_addc_co_u32_e32 v17, vcc, 0, v19, vcc
	global_store_dword v[16:17], v20, off offset:64
.LBB0_686:
	s_or_b64 exec, exec, s[10:11]
	v_mul_f32_e32 v16, v38, v12
	s_waitcnt lgkmcnt(0)
	s_nop 1
	v_mov_b32_dpp v17, v16 quad_perm:[1,0,3,2] row_mask:0xf bank_mask:0xf
	s_and_saveexec_b64 s[10:11], s[6:7]
	s_cbranch_execz .LBB0_688
	v_lshl_add_u64 v[18:19], s[8:9], 0, v[2:3]
	s_waitcnt lgkmcnt(0)
	v_cvt_pk_bf16_f32 v20, v16, v17
	v_add_co_u32_e32 v16, vcc, 0x8000, v18
	s_nop 1
	v_addc_co_u32_e32 v17, vcc, 0, v19, vcc
	global_store_dword v[16:17], v20, off offset:128
.LBB0_688:
	s_or_b64 exec, exec, s[10:11]
	v_mul_f32_e32 v12, v22, v12
	s_nop 1
	v_mov_b32_dpp v16, v12 quad_perm:[1,0,3,2] row_mask:0xf bank_mask:0xf
	s_and_saveexec_b64 s[10:11], s[6:7]
	s_cbranch_execz .LBB0_690
	v_lshl_add_u64 v[18:19], s[8:9], 0, v[2:3]
	s_waitcnt lgkmcnt(0)
	v_cvt_pk_bf16_f32 v12, v12, v16
	v_add_co_u32_e32 v16, vcc, 0x8000, v18
	s_nop 1
	v_addc_co_u32_e32 v17, vcc, 0, v19, vcc
	global_store_dword v[16:17], v12, off offset:192
.LBB0_690:
	s_or_b64 exec, exec, s[10:11]
	v_rcp_f32_e32 v12, v13
	s_nop 0
	v_mul_f32_e32 v13, v71, v12
	s_waitcnt lgkmcnt(0)
	s_nop 1
	v_mov_b32_dpp v16, v13 quad_perm:[1,0,3,2] row_mask:0xf bank_mask:0xf
	s_and_saveexec_b64 s[10:11], s[6:7]
	s_cbranch_execz .LBB0_692
	v_lshl_add_u64 v[18:19], s[8:9], 0, v[2:3]
	s_waitcnt lgkmcnt(0)
	v_cvt_pk_bf16_f32 v13, v13, v16
	v_add_co_u32_e32 v16, vcc, 0x9000, v18
	s_nop 1
	v_addc_co_u32_e32 v17, vcc, 0, v19, vcc
	global_store_dword v[16:17], v13, off
.LBB0_692:
	s_or_b64 exec, exec, s[10:11]
	v_mul_f32_e32 v13, v55, v12
	s_waitcnt lgkmcnt(0)
	s_nop 1
	v_mov_b32_dpp v16, v13 quad_perm:[1,0,3,2] row_mask:0xf bank_mask:0xf
	s_and_saveexec_b64 s[10:11], s[6:7]
	s_cbranch_execz .LBB0_694
	v_lshl_add_u64 v[18:19], s[8:9], 0, v[2:3]
	s_waitcnt lgkmcnt(0)
	v_cvt_pk_bf16_f32 v13, v13, v16
	v_add_co_u32_e32 v16, vcc, 0x9000, v18
	s_nop 1
	v_addc_co_u32_e32 v17, vcc, 0, v19, vcc
	global_store_dword v[16:17], v13, off offset:64
.LBB0_694:
	s_or_b64 exec, exec, s[10:11]
	v_mul_f32_e32 v13, v39, v12
	s_waitcnt lgkmcnt(0)
	s_nop 1
	v_mov_b32_dpp v16, v13 quad_perm:[1,0,3,2] row_mask:0xf bank_mask:0xf
	s_and_saveexec_b64 s[10:11], s[6:7]
	s_cbranch_execz .LBB0_696
	v_lshl_add_u64 v[18:19], s[8:9], 0, v[2:3]
	s_waitcnt lgkmcnt(0)
	v_cvt_pk_bf16_f32 v13, v13, v16
	v_add_co_u32_e32 v16, vcc, 0x9000, v18
	s_nop 1
	v_addc_co_u32_e32 v17, vcc, 0, v19, vcc
	global_store_dword v[16:17], v13, off offset:128
.LBB0_696:
	s_or_b64 exec, exec, s[10:11]
	v_mul_f32_e32 v12, v23, v12
	s_nop 1
	v_mov_b32_dpp v13, v12 quad_perm:[1,0,3,2] row_mask:0xf bank_mask:0xf
	s_and_saveexec_b64 s[10:11], s[6:7]
	s_cbranch_execz .LBB0_698
	s_waitcnt lgkmcnt(1)
	v_lshl_add_u64 v[16:17], s[8:9], 0, v[2:3]
	s_waitcnt lgkmcnt(0)
	v_cvt_pk_bf16_f32 v18, v12, v13
	v_add_co_u32_e32 v12, vcc, 0x9000, v16
	s_nop 1
	v_addc_co_u32_e32 v13, vcc, 0, v17, vcc
	global_store_dword v[12:13], v18, off offset:192
; __device__ __forceinline__ int crow(int r, int hi) { return (r & 3) + 8 * (r >> 2) + 4 * hi; }
; __device__ __forceinline__ unsigned cvtpk(float lo, float hi) { unsigned r; asm volatile("v_cvt_pk_bf16_f32 %0, %1, %2" : "=v"(r) : "v"(lo), "v"(hi)); return r; }
;     static __device__ __forceinline__ void block(const BlockRef& cur, const BlockRef& nxt, int skv, char* lds, Seam& S) {
;     ...
;         for (int r = 0; r < 16; ++r) rli[r] = __builtin_amdgcn_rcpf(li_l[crow(r, hi)]);
;         bf16* Ow = cur.O + (unsigned)((wid * QBLK) * LDO);
; #pragma unroll
;         for (int r = 0; r < 16; ++r) { const int orow = crow(r, hi);
; #pragma unroll
;             for (int d0 = 0; d0 < 4; ++d0) { const float v = o[d0][r] * rli[r];
;                 const float vn = __shfl_xor(v, 1);
;                 if ((r32 & 1) == 0) *(unsigned*)(Ow + (unsigned)(orow * LDO + d0 * 32 + r32)) = cvtpk(v, vn); } }
.LBB0_698:
	s_or_b64 exec, exec, s[10:11]
	v_rcp_f32_e32 v12, v14
	s_waitcnt lgkmcnt(0)
	v_mul_f32_e32 v13, v72, v12
	s_nop 1
	v_mov_b32_dpp v14, v13 quad_perm:[1,0,3,2] row_mask:0xf bank_mask:0xf
	s_and_saveexec_b64 s[10:11], s[6:7]
	s_cbranch_execz .LBB0_700
	v_lshl_add_u64 v[16:17], s[8:9], 0, v[2:3]
	v_add_co_u32_e32 v16, vcc, 0xa000, v16
	s_waitcnt lgkmcnt(0)
	v_cvt_pk_bf16_f32 v13, v13, v14
	s_nop 0
	v_addc_co_u32_e32 v17, vcc, 0, v17, vcc
	global_store_dword v[16:17], v13, off
.LBB0_700:
	s_or_b64 exec, exec, s[10:11]
	v_mul_f32_e32 v13, v56, v12
	s_waitcnt lgkmcnt(0)
	s_nop 1
	v_mov_b32_dpp v14, v13 quad_perm:[1,0,3,2] row_mask:0xf bank_mask:0xf
	s_and_saveexec_b64 s[10:11], s[6:7]
	s_cbranch_execz .LBB0_702
	v_lshl_add_u64 v[16:17], s[8:9], 0, v[2:3]
	v_add_co_u32_e32 v16, vcc, 0xa000, v16
	s_waitcnt lgkmcnt(0)
	v_cvt_pk_bf16_f32 v13, v13, v14
	s_nop 0
	v_addc_co_u32_e32 v17, vcc, 0, v17, vcc
	global_store_dword v[16:17], v13, off offset:64
.LBB0_702:
	s_or_b64 exec, exec, s[10:11]
	v_mul_f32_e32 v13, v40, v12
	s_waitcnt lgkmcnt(0)
	s_nop 1
	v_mov_b32_dpp v14, v13 quad_perm:[1,0,3,2] row_mask:0xf bank_mask:0xf
	s_and_saveexec_b64 s[10:11], s[6:7]
	s_cbranch_execz .LBB0_704
	v_lshl_add_u64 v[16:17], s[8:9], 0, v[2:3]
	v_add_co_u32_e32 v16, vcc, 0xa000, v16
	s_waitcnt lgkmcnt(0)
	v_cvt_pk_bf16_f32 v13, v13, v14
	s_nop 0
	v_addc_co_u32_e32 v17, vcc, 0, v17, vcc
	global_store_dword v[16:17], v13, off offset:128
.LBB0_704:
	s_or_b64 exec, exec, s[10:11]
	v_mul_f32_e32 v12, v24, v12
	s_nop 1
	v_mov_b32_dpp v13, v12 quad_perm:[1,0,3,2] row_mask:0xf bank_mask:0xf
	s_and_saveexec_b64 s[10:11], s[6:7]
	s_cbranch_execz .LBB0_706
	v_lshl_add_u64 v[16:17], s[8:9], 0, v[2:3]
	s_waitcnt lgkmcnt(0)
	v_cvt_pk_bf16_f32 v14, v12, v13
	v_add_co_u32_e32 v12, vcc, 0xa000, v16
	s_nop 1
	v_addc_co_u32_e32 v13, vcc, 0, v17, vcc
	global_store_dword v[12:13], v14, off offset:192
.LBB0_706:
	s_or_b64 exec, exec, s[10:11]
	v_rcp_f32_e32 v12, v15
	s_waitcnt lgkmcnt(0)
	v_mul_f32_e32 v13, v73, v12
	s_nop 1
	v_mov_b32_dpp v14, v13 quad_perm:[1,0,3,2] row_mask:0xf bank_mask:0xf
	s_and_saveexec_b64 s[10:11], s[6:7]
	s_cbranch_execz .LBB0_708
	v_lshl_add_u64 v[16:17], s[8:9], 0, v[2:3]
	s_waitcnt lgkmcnt(0)
	v_cvt_pk_bf16_f32 v13, v13, v14
	v_add_co_u32_e32 v14, vcc, 0xb000, v16
	s_nop 1
	v_addc_co_u32_e32 v15, vcc, 0, v17, vcc
	global_store_dword v[14:15], v13, off
.LBB0_708:
	s_or_b64 exec, exec, s[10:11]
	v_mul_f32_e32 v13, v57, v12
	s_waitcnt lgkmcnt(0)
	s_nop 1
	v_mov_b32_dpp v14, v13 quad_perm:[1,0,3,2] row_mask:0xf bank_mask:0xf
	s_and_saveexec_b64 s[10:11], s[6:7]
	s_cbranch_execz .LBB0_710
	v_lshl_add_u64 v[16:17], s[8:9], 0, v[2:3]
	s_waitcnt lgkmcnt(0)
	v_cvt_pk_bf16_f32 v13, v13, v14
	v_add_co_u32_e32 v14, vcc, 0xb000, v16
	s_nop 1
	v_addc_co_u32_e32 v15, vcc, 0, v17, vcc
	global_store_dword v[14:15], v13, off offset:64
.LBB0_710:
	s_or_b64 exec, exec, s[10:11]
	v_mul_f32_e32 v13, v41, v12
	s_waitcnt lgkmcnt(0)
	s_nop 1
	v_mov_b32_dpp v14, v13 quad_perm:[1,0,3,2] row_mask:0xf bank_mask:0xf
	s_and_saveexec_b64 s[10:11], s[6:7]
	s_cbranch_execz .LBB0_712
	v_lshl_add_u64 v[16:17], s[8:9], 0, v[2:3]
	s_waitcnt lgkmcnt(0)
	v_cvt_pk_bf16_f32 v13, v13, v14
	v_add_co_u32_e32 v14, vcc, 0xb000, v16
	s_nop 1
	v_addc_co_u32_e32 v15, vcc, 0, v17, vcc
	global_store_dword v[14:15], v13, off offset:128
.LBB0_712:
	s_or_b64 exec, exec, s[10:11]
	v_mul_f32_e32 v12, v25, v12
	s_nop 1
	v_mov_b32_dpp v13, v12 quad_perm:[1,0,3,2] row_mask:0xf bank_mask:0xf
	s_and_saveexec_b64 s[10:11], s[6:7]
	s_cbranch_execz .LBB0_714
	s_waitcnt lgkmcnt(1)
	v_lshl_add_u64 v[14:15], s[8:9], 0, v[2:3]
	s_waitcnt lgkmcnt(0)
	v_cvt_pk_bf16_f32 v16, v12, v13
	v_add_co_u32_e32 v12, vcc, 0xb000, v14
	s_nop 1
	v_addc_co_u32_e32 v13, vcc, 0, v15, vcc
	global_store_dword v[12:13], v16, off offset:192
.LBB0_714:
	s_or_b64 exec, exec, s[10:11]
	v_rcp_f32_e32 v8, v8
	s_nop 0
	v_mul_f32_e32 v12, v74, v8
	s_waitcnt lgkmcnt(0)
	s_nop 1
	v_mov_b32_dpp v13, v12 quad_perm:[1,0,3,2] row_mask:0xf bank_mask:0xf
	s_and_saveexec_b64 s[10:11], s[6:7]
	s_cbranch_execz .LBB0_716
	v_lshl_add_u64 v[14:15], s[8:9], 0, v[2:3]
	s_waitcnt lgkmcnt(0)
	v_cvt_pk_bf16_f32 v16, v12, v13
	v_add_co_u32_e32 v12, vcc, 0x10000, v14
	s_nop 1
	v_addc_co_u32_e32 v13, vcc, 0, v15, vcc
	global_store_dword v[12:13], v16, off
.LBB0_716:
	s_or_b64 exec, exec, s[10:11]
	v_mul_f32_e32 v12, v58, v8
	s_waitcnt lgkmcnt(0)
	s_nop 1
	v_mov_b32_dpp v13, v12 quad_perm:[1,0,3,2] row_mask:0xf bank_mask:0xf
	s_and_saveexec_b64 s[10:11], s[6:7]
	s_cbranch_execz .LBB0_718
	v_lshl_add_u64 v[14:15], s[8:9], 0, v[2:3]
	s_waitcnt lgkmcnt(0)
	v_cvt_pk_bf16_f32 v16, v12, v13
	v_add_co_u32_e32 v12, vcc, 0x10000, v14
	s_nop 1
	v_addc_co_u32_e32 v13, vcc, 0, v15, vcc
	global_store_dword v[12:13], v16, off offset:64
.LBB0_718:
	s_or_b64 exec, exec, s[10:11]
	v_mul_f32_e32 v12, v42, v8
	s_waitcnt lgkmcnt(0)
	s_nop 1
	v_mov_b32_dpp v13, v12 quad_perm:[1,0,3,2] row_mask:0xf bank_mask:0xf
	s_and_saveexec_b64 s[10:11], s[6:7]
	s_cbranch_execz .LBB0_720
	v_lshl_add_u64 v[14:15], s[8:9], 0, v[2:3]
	s_waitcnt lgkmcnt(0)
	v_cvt_pk_bf16_f32 v16, v12, v13
	v_add_co_u32_e32 v12, vcc, 0x10000, v14
	s_nop 1
	v_addc_co_u32_e32 v13, vcc, 0, v15, vcc
	global_store_dword v[12:13], v16, off offset:128
.LBB0_720:
	s_or_b64 exec, exec, s[10:11]
	v_mul_f32_e32 v8, v26, v8
	s_nop 1
	v_mov_b32_dpp v12, v8 quad_perm:[1,0,3,2] row_mask:0xf bank_mask:0xf
	s_and_saveexec_b64 s[10:11], s[6:7]
	s_cbranch_execz .LBB0_722
	v_lshl_add_u64 v[14:15], s[8:9], 0, v[2:3]
	s_waitcnt lgkmcnt(0)
	v_cvt_pk_bf16_f32 v8, v8, v12
	v_add_co_u32_e32 v12, vcc, 0x10000, v14
	s_nop 1
	v_addc_co_u32_e32 v13, vcc, 0, v15, vcc
	global_store_dword v[12:13], v8, off offset:192
; __device__ __forceinline__ int crow(int r, int hi) { return (r & 3) + 8 * (r >> 2) + 4 * hi; }
; __device__ __forceinline__ unsigned cvtpk(float lo, float hi) { unsigned r; asm volatile("v_cvt_pk_bf16_f32 %0, %1, %2" : "=v"(r) : "v"(lo), "v"(hi)); return r; }
;     static __device__ __forceinline__ void block(const BlockRef& cur, const BlockRef& nxt, int skv, char* lds, Seam& S) {
;     ...
;         for (int r = 0; r < 16; ++r) rli[r] = __builtin_amdgcn_rcpf(li_l[crow(r, hi)]);
;         bf16* Ow = cur.O + (unsigned)((wid * QBLK) * LDO);
; #pragma unroll
;         for (int r = 0; r < 16; ++r) { const int orow = crow(r, hi);
; #pragma unroll
;             for (int d0 = 0; d0 < 4; ++d0) { const float v = o[d0][r] * rli[r];
;                 const float vn = __shfl_xor(v, 1);
;                 if ((r32 & 1) == 0) *(unsigned*)(Ow + (unsigned)(orow * LDO + d0 * 32 + r32)) = cvtpk(v, vn); } }
.LBB0_722:
	s_or_b64 exec, exec, s[10:11]
	v_rcp_f32_e32 v8, v9
	s_nop 0
	v_mul_f32_e32 v9, v75, v8
	s_waitcnt lgkmcnt(0)
	s_nop 1
	v_mov_b32_dpp v12, v9 quad_perm:[1,0,3,2] row_mask:0xf bank_mask:0xf
	s_and_saveexec_b64 s[10:11], s[6:7]
	s_cbranch_execz .LBB0_724
	v_lshl_add_u64 v[14:15], s[8:9], 0, v[2:3]
	s_waitcnt lgkmcnt(0)
	v_cvt_pk_bf16_f32 v9, v9, v12
	v_add_co_u32_e32 v12, vcc, 0x11000, v14
	s_nop 1
	v_addc_co_u32_e32 v13, vcc, 0, v15, vcc
	global_store_dword v[12:13], v9, off
.LBB0_724:
	s_or_b64 exec, exec, s[10:11]
	v_mul_f32_e32 v9, v59, v8
	s_waitcnt lgkmcnt(0)
	s_nop 1
	v_mov_b32_dpp v12, v9 quad_perm:[1,0,3,2] row_mask:0xf bank_mask:0xf
	s_and_saveexec_b64 s[10:11], s[6:7]
	s_cbranch_execz .LBB0_726
	v_lshl_add_u64 v[14:15], s[8:9], 0, v[2:3]
	s_waitcnt lgkmcnt(0)
	v_cvt_pk_bf16_f32 v9, v9, v12
	v_add_co_u32_e32 v12, vcc, 0x11000, v14
	s_nop 1
	v_addc_co_u32_e32 v13, vcc, 0, v15, vcc
	global_store_dword v[12:13], v9, off offset:64
.LBB0_726:
	s_or_b64 exec, exec, s[10:11]
	v_mul_f32_e32 v9, v43, v8
	s_waitcnt lgkmcnt(0)
	s_nop 1
	v_mov_b32_dpp v12, v9 quad_perm:[1,0,3,2] row_mask:0xf bank_mask:0xf
	s_and_saveexec_b64 s[10:11], s[6:7]
	s_cbranch_execz .LBB0_728
	v_lshl_add_u64 v[14:15], s[8:9], 0, v[2:3]
	s_waitcnt lgkmcnt(0)
	v_cvt_pk_bf16_f32 v9, v9, v12
	v_add_co_u32_e32 v12, vcc, 0x11000, v14
	s_nop 1
	v_addc_co_u32_e32 v13, vcc, 0, v15, vcc
	global_store_dword v[12:13], v9, off offset:128
.LBB0_728:
	s_or_b64 exec, exec, s[10:11]
	v_mul_f32_e32 v8, v27, v8
	s_nop 1
	v_mov_b32_dpp v9, v8 quad_perm:[1,0,3,2] row_mask:0xf bank_mask:0xf
	s_and_saveexec_b64 s[10:11], s[6:7]
	s_cbranch_execz .LBB0_730
	s_waitcnt lgkmcnt(1)
	v_lshl_add_u64 v[12:13], s[8:9], 0, v[2:3]
	s_waitcnt lgkmcnt(0)
	v_cvt_pk_bf16_f32 v14, v8, v9
	v_add_co_u32_e32 v8, vcc, 0x11000, v12
	s_nop 1
	v_addc_co_u32_e32 v9, vcc, 0, v13, vcc
	global_store_dword v[8:9], v14, off offset:192
.LBB0_730:
	s_or_b64 exec, exec, s[10:11]
	v_rcp_f32_e32 v8, v10
	s_waitcnt lgkmcnt(0)
	v_mul_f32_e32 v9, v76, v8
	s_nop 1
	v_mov_b32_dpp v10, v9 quad_perm:[1,0,3,2] row_mask:0xf bank_mask:0xf
	s_and_saveexec_b64 s[10:11], s[6:7]
	s_cbranch_execz .LBB0_732
	v_lshl_add_u64 v[12:13], s[8:9], 0, v[2:3]
	v_add_co_u32_e32 v12, vcc, 0x12000, v12
	s_waitcnt lgkmcnt(0)
	v_cvt_pk_bf16_f32 v9, v9, v10
	s_nop 0
	v_addc_co_u32_e32 v13, vcc, 0, v13, vcc
	global_store_dword v[12:13], v9, off
.LBB0_732:
	s_or_b64 exec, exec, s[10:11]
	v_mul_f32_e32 v9, v60, v8
	s_waitcnt lgkmcnt(0)
	s_nop 1
	v_mov_b32_dpp v10, v9 quad_perm:[1,0,3,2] row_mask:0xf bank_mask:0xf
	s_and_saveexec_b64 s[10:11], s[6:7]
	s_cbranch_execz .LBB0_734
	v_lshl_add_u64 v[12:13], s[8:9], 0, v[2:3]
	v_add_co_u32_e32 v12, vcc, 0x12000, v12
	s_waitcnt lgkmcnt(0)
	v_cvt_pk_bf16_f32 v9, v9, v10
	s_nop 0
	v_addc_co_u32_e32 v13, vcc, 0, v13, vcc
	global_store_dword v[12:13], v9, off offset:64
.LBB0_734:
	s_or_b64 exec, exec, s[10:11]
	v_mul_f32_e32 v9, v44, v8
	s_waitcnt lgkmcnt(0)
	s_nop 1
	v_mov_b32_dpp v10, v9 quad_perm:[1,0,3,2] row_mask:0xf bank_mask:0xf
	s_and_saveexec_b64 s[10:11], s[6:7]
	s_cbranch_execz .LBB0_736
	v_lshl_add_u64 v[12:13], s[8:9], 0, v[2:3]
	v_add_co_u32_e32 v12, vcc, 0x12000, v12
	s_waitcnt lgkmcnt(0)
	v_cvt_pk_bf16_f32 v9, v9, v10
	s_nop 0
	v_addc_co_u32_e32 v13, vcc, 0, v13, vcc
	global_store_dword v[12:13], v9, off offset:128
.LBB0_736:
	s_or_b64 exec, exec, s[10:11]
	v_mul_f32_e32 v8, v28, v8
	s_nop 1
	v_mov_b32_dpp v9, v8 quad_perm:[1,0,3,2] row_mask:0xf bank_mask:0xf
	s_and_saveexec_b64 s[10:11], s[6:7]
	s_cbranch_execz .LBB0_738
	v_lshl_add_u64 v[12:13], s[8:9], 0, v[2:3]
	s_waitcnt lgkmcnt(0)
	v_cvt_pk_bf16_f32 v10, v8, v9
	v_add_co_u32_e32 v8, vcc, 0x12000, v12
	s_nop 1
	v_addc_co_u32_e32 v9, vcc, 0, v13, vcc
	global_store_dword v[8:9], v10, off offset:192
.LBB0_738:
	s_or_b64 exec, exec, s[10:11]
	v_rcp_f32_e32 v8, v11
	s_waitcnt lgkmcnt(0)
	v_mul_f32_e32 v9, v77, v8
	s_nop 1
	v_mov_b32_dpp v10, v9 quad_perm:[1,0,3,2] row_mask:0xf bank_mask:0xf
	s_and_saveexec_b64 s[10:11], s[6:7]
	s_cbranch_execz .LBB0_740
	v_lshl_add_u64 v[12:13], s[8:9], 0, v[2:3]
	s_waitcnt lgkmcnt(0)
	v_cvt_pk_bf16_f32 v9, v9, v10
	v_add_co_u32_e32 v10, vcc, 0x13000, v12
	s_nop 1
	v_addc_co_u32_e32 v11, vcc, 0, v13, vcc
	global_store_dword v[10:11], v9, off
.LBB0_740:
	s_or_b64 exec, exec, s[10:11]
	v_mul_f32_e32 v9, v61, v8
	s_waitcnt lgkmcnt(0)
	s_nop 1
	v_mov_b32_dpp v10, v9 quad_perm:[1,0,3,2] row_mask:0xf bank_mask:0xf
	s_and_saveexec_b64 s[10:11], s[6:7]
	s_cbranch_execz .LBB0_742
	v_lshl_add_u64 v[12:13], s[8:9], 0, v[2:3]
	s_waitcnt lgkmcnt(0)
	v_cvt_pk_bf16_f32 v9, v9, v10
	v_add_co_u32_e32 v10, vcc, 0x13000, v12
	s_nop 1
	v_addc_co_u32_e32 v11, vcc, 0, v13, vcc
	global_store_dword v[10:11], v9, off offset:64
.LBB0_742:
	s_or_b64 exec, exec, s[10:11]
	v_mul_f32_e32 v9, v45, v8
	s_waitcnt lgkmcnt(0)
	s_nop 1
	v_mov_b32_dpp v10, v9 quad_perm:[1,0,3,2] row_mask:0xf bank_mask:0xf
	s_and_saveexec_b64 s[10:11], s[6:7]
	s_cbranch_execz .LBB0_744
	v_lshl_add_u64 v[12:13], s[8:9], 0, v[2:3]
	s_waitcnt lgkmcnt(0)
	v_cvt_pk_bf16_f32 v9, v9, v10
	v_add_co_u32_e32 v10, vcc, 0x13000, v12
	s_nop 1
	v_addc_co_u32_e32 v11, vcc, 0, v13, vcc
	global_store_dword v[10:11], v9, off offset:128
.LBB0_744:
	s_or_b64 exec, exec, s[10:11]
	v_mul_f32_e32 v8, v29, v8
	s_nop 1
	v_mov_b32_dpp v9, v8 quad_perm:[1,0,3,2] row_mask:0xf bank_mask:0xf
	s_and_saveexec_b64 s[10:11], s[6:7]
	s_cbranch_execz .LBB0_746
	s_waitcnt lgkmcnt(1)
	v_lshl_add_u64 v[10:11], s[8:9], 0, v[2:3]
	s_waitcnt lgkmcnt(0)
	v_cvt_pk_bf16_f32 v12, v8, v9
	v_add_co_u32_e32 v8, vcc, 0x13000, v10
	s_nop 1
	v_addc_co_u32_e32 v9, vcc, 0, v11, vcc
	global_store_dword v[8:9], v12, off offset:192
; __device__ __forceinline__ int crow(int r, int hi) { return (r & 3) + 8 * (r >> 2) + 4 * hi; }
; __device__ __forceinline__ unsigned cvtpk(float lo, float hi) { unsigned r; asm volatile("v_cvt_pk_bf16_f32 %0, %1, %2" : "=v"(r) : "v"(lo), "v"(hi)); return r; }
;     static __device__ __forceinline__ void block(const BlockRef& cur, const BlockRef& nxt, int skv, char* lds, Seam& S) {
;     ...
;         for (int r = 0; r < 16; ++r) rli[r] = __builtin_amdgcn_rcpf(li_l[crow(r, hi)]);
;         bf16* Ow = cur.O + (unsigned)((wid * QBLK) * LDO);
; #pragma unroll
;         for (int r = 0; r < 16; ++r) { const int orow = crow(r, hi);
; #pragma unroll
;             for (int d0 = 0; d0 < 4; ++d0) { const float v = o[d0][r] * rli[r];
;                 const float vn = __shfl_xor(v, 1);
;                 if ((r32 & 1) == 0) *(unsigned*)(Ow + (unsigned)(orow * LDO + d0 * 32 + r32)) = cvtpk(v, vn); } }
.LBB0_746:
	s_or_b64 exec, exec, s[10:11]
	v_rcp_f32_e32 v4, v4
	s_nop 0
	v_mul_f32_e32 v8, v78, v4
	s_waitcnt lgkmcnt(0)
	s_nop 1
	v_mov_b32_dpp v9, v8 quad_perm:[1,0,3,2] row_mask:0xf bank_mask:0xf
	s_and_saveexec_b64 s[10:11], s[6:7]
	s_cbranch_execz .LBB0_748
	v_lshl_add_u64 v[10:11], s[8:9], 0, v[2:3]
	s_waitcnt lgkmcnt(0)
	v_cvt_pk_bf16_f32 v12, v8, v9
	v_add_co_u32_e32 v8, vcc, 0x18000, v10
	s_nop 1
	v_addc_co_u32_e32 v9, vcc, 0, v11, vcc
	global_store_dword v[8:9], v12, off
.LBB0_748:
	s_or_b64 exec, exec, s[10:11]
	v_mul_f32_e32 v8, v62, v4
	s_waitcnt lgkmcnt(0)
	s_nop 1
	v_mov_b32_dpp v9, v8 quad_perm:[1,0,3,2] row_mask:0xf bank_mask:0xf
	s_and_saveexec_b64 s[10:11], s[6:7]
	s_cbranch_execz .LBB0_750
	v_lshl_add_u64 v[10:11], s[8:9], 0, v[2:3]
	s_waitcnt lgkmcnt(0)
	v_cvt_pk_bf16_f32 v12, v8, v9
	v_add_co_u32_e32 v8, vcc, 0x18000, v10
	s_nop 1
	v_addc_co_u32_e32 v9, vcc, 0, v11, vcc
	global_store_dword v[8:9], v12, off offset:64
.LBB0_750:
	s_or_b64 exec, exec, s[10:11]
	v_mul_f32_e32 v8, v46, v4
	s_waitcnt lgkmcnt(0)
	s_nop 1
	v_mov_b32_dpp v9, v8 quad_perm:[1,0,3,2] row_mask:0xf bank_mask:0xf
	s_and_saveexec_b64 s[10:11], s[6:7]
	s_cbranch_execz .LBB0_752
	v_lshl_add_u64 v[10:11], s[8:9], 0, v[2:3]
	s_waitcnt lgkmcnt(0)
	v_cvt_pk_bf16_f32 v12, v8, v9
	v_add_co_u32_e32 v8, vcc, 0x18000, v10
	s_nop 1
	v_addc_co_u32_e32 v9, vcc, 0, v11, vcc
	global_store_dword v[8:9], v12, off offset:128
.LBB0_752:
	s_or_b64 exec, exec, s[10:11]
	v_mul_f32_e32 v4, v30, v4
	s_nop 1
	v_mov_b32_dpp v8, v4 quad_perm:[1,0,3,2] row_mask:0xf bank_mask:0xf
	s_and_saveexec_b64 s[10:11], s[6:7]
	s_cbranch_execz .LBB0_754
	v_lshl_add_u64 v[10:11], s[8:9], 0, v[2:3]
	s_waitcnt lgkmcnt(0)
	v_cvt_pk_bf16_f32 v4, v4, v8
	v_add_co_u32_e32 v8, vcc, 0x18000, v10
	s_nop 1
	v_addc_co_u32_e32 v9, vcc, 0, v11, vcc
	global_store_dword v[8:9], v4, off offset:192
.LBB0_754:
	s_or_b64 exec, exec, s[10:11]
	v_rcp_f32_e32 v4, v5
	s_nop 0
	v_mul_f32_e32 v5, v79, v4
	s_waitcnt lgkmcnt(0)
	s_nop 1
	v_mov_b32_dpp v8, v5 quad_perm:[1,0,3,2] row_mask:0xf bank_mask:0xf
	s_and_saveexec_b64 s[10:11], s[6:7]
	s_cbranch_execz .LBB0_756
	v_lshl_add_u64 v[10:11], s[8:9], 0, v[2:3]
	s_waitcnt lgkmcnt(0)
	v_cvt_pk_bf16_f32 v5, v5, v8
	v_add_co_u32_e32 v8, vcc, 0x19000, v10
	s_nop 1
	v_addc_co_u32_e32 v9, vcc, 0, v11, vcc
	global_store_dword v[8:9], v5, off
.LBB0_756:
	s_or_b64 exec, exec, s[10:11]
	v_mul_f32_e32 v5, v63, v4
	s_waitcnt lgkmcnt(0)
	s_nop 1
	v_mov_b32_dpp v8, v5 quad_perm:[1,0,3,2] row_mask:0xf bank_mask:0xf
	s_and_saveexec_b64 s[10:11], s[6:7]
	s_cbranch_execz .LBB0_758
	v_lshl_add_u64 v[10:11], s[8:9], 0, v[2:3]
	s_waitcnt lgkmcnt(0)
	v_cvt_pk_bf16_f32 v5, v5, v8
	v_add_co_u32_e32 v8, vcc, 0x19000, v10
	s_nop 1
	v_addc_co_u32_e32 v9, vcc, 0, v11, vcc
	global_store_dword v[8:9], v5, off offset:64
.LBB0_758:
	s_or_b64 exec, exec, s[10:11]
	v_mul_f32_e32 v5, v47, v4
	s_waitcnt lgkmcnt(0)
	s_nop 1
	v_mov_b32_dpp v8, v5 quad_perm:[1,0,3,2] row_mask:0xf bank_mask:0xf
	s_and_saveexec_b64 s[10:11], s[6:7]
	s_cbranch_execz .LBB0_760
	v_lshl_add_u64 v[10:11], s[8:9], 0, v[2:3]
	s_waitcnt lgkmcnt(0)
	v_cvt_pk_bf16_f32 v5, v5, v8
	v_add_co_u32_e32 v8, vcc, 0x19000, v10
	s_nop 1
	v_addc_co_u32_e32 v9, vcc, 0, v11, vcc
	global_store_dword v[8:9], v5, off offset:128
.LBB0_760:
	s_or_b64 exec, exec, s[10:11]
	v_mul_f32_e32 v4, v31, v4
	s_nop 1
	v_mov_b32_dpp v5, v4 quad_perm:[1,0,3,2] row_mask:0xf bank_mask:0xf
	s_and_saveexec_b64 s[10:11], s[6:7]
	s_cbranch_execz .LBB0_762
	s_waitcnt lgkmcnt(1)
	v_lshl_add_u64 v[8:9], s[8:9], 0, v[2:3]
	s_waitcnt lgkmcnt(0)
	v_cvt_pk_bf16_f32 v10, v4, v5
	v_add_co_u32_e32 v4, vcc, 0x19000, v8
	s_nop 1
	v_addc_co_u32_e32 v5, vcc, 0, v9, vcc
	global_store_dword v[4:5], v10, off offset:192
; __device__ __forceinline__ int crow(int r, int hi) { return (r & 3) + 8 * (r >> 2) + 4 * hi; }
; __device__ __forceinline__ unsigned cvtpk(float lo, float hi) { unsigned r; asm volatile("v_cvt_pk_bf16_f32 %0, %1, %2" : "=v"(r) : "v"(lo), "v"(hi)); return r; }
;     static __device__ __forceinline__ void block(const BlockRef& cur, const BlockRef& nxt, int skv, char* lds, Seam& S) {
;     ...
;         for (int r = 0; r < 16; ++r) rli[r] = __builtin_amdgcn_rcpf(li_l[crow(r, hi)]);
;         bf16* Ow = cur.O + (unsigned)((wid * QBLK) * LDO);
; #pragma unroll
;         for (int r = 0; r < 16; ++r) { const int orow = crow(r, hi);
; #pragma unroll
;             for (int d0 = 0; d0 < 4; ++d0) { const float v = o[d0][r] * rli[r];
;                 const float vn = __shfl_xor(v, 1);
;                 if ((r32 & 1) == 0) *(unsigned*)(Ow + (unsigned)(orow * LDO + d0 * 32 + r32)) = cvtpk(v, vn); } }
.LBB0_762:
	s_or_b64 exec, exec, s[10:11]
	v_rcp_f32_e32 v4, v6
	s_waitcnt lgkmcnt(0)
	v_mul_f32_e32 v5, v80, v4
	s_nop 1
	v_mov_b32_dpp v6, v5 quad_perm:[1,0,3,2] row_mask:0xf bank_mask:0xf
	s_and_saveexec_b64 s[10:11], s[6:7]
	s_cbranch_execz .LBB0_764
	v_lshl_add_u64 v[8:9], s[8:9], 0, v[2:3]
	v_add_co_u32_e32 v8, vcc, 0x1a000, v8
	s_waitcnt lgkmcnt(0)
	v_cvt_pk_bf16_f32 v5, v5, v6
	s_nop 0
	v_addc_co_u32_e32 v9, vcc, 0, v9, vcc
	global_store_dword v[8:9], v5, off
.LBB0_764:
	s_or_b64 exec, exec, s[10:11]
	v_mul_f32_e32 v5, v64, v4
	s_waitcnt lgkmcnt(0)
	s_nop 1
	v_mov_b32_dpp v6, v5 quad_perm:[1,0,3,2] row_mask:0xf bank_mask:0xf
	s_and_saveexec_b64 s[10:11], s[6:7]
	s_cbranch_execz .LBB0_766
	v_lshl_add_u64 v[8:9], s[8:9], 0, v[2:3]
	v_add_co_u32_e32 v8, vcc, 0x1a000, v8
	s_waitcnt lgkmcnt(0)
	v_cvt_pk_bf16_f32 v5, v5, v6
	s_nop 0
	v_addc_co_u32_e32 v9, vcc, 0, v9, vcc
	global_store_dword v[8:9], v5, off offset:64
.LBB0_766:
	s_or_b64 exec, exec, s[10:11]
	v_mul_f32_e32 v5, v48, v4
	s_waitcnt lgkmcnt(0)
	s_nop 1
	v_mov_b32_dpp v6, v5 quad_perm:[1,0,3,2] row_mask:0xf bank_mask:0xf
	s_and_saveexec_b64 s[10:11], s[6:7]
	s_cbranch_execz .LBB0_768
	v_lshl_add_u64 v[8:9], s[8:9], 0, v[2:3]
	v_add_co_u32_e32 v8, vcc, 0x1a000, v8
	s_waitcnt lgkmcnt(0)
	v_cvt_pk_bf16_f32 v5, v5, v6
	s_nop 0
	v_addc_co_u32_e32 v9, vcc, 0, v9, vcc
	global_store_dword v[8:9], v5, off offset:128
.LBB0_768:
	s_or_b64 exec, exec, s[10:11]
	v_mul_f32_e32 v4, v32, v4
	s_nop 1
	v_mov_b32_dpp v5, v4 quad_perm:[1,0,3,2] row_mask:0xf bank_mask:0xf
	s_and_saveexec_b64 s[10:11], s[6:7]
	s_cbranch_execz .LBB0_770
	v_lshl_add_u64 v[8:9], s[8:9], 0, v[2:3]
	s_waitcnt lgkmcnt(0)
	v_cvt_pk_bf16_f32 v6, v4, v5
	v_add_co_u32_e32 v4, vcc, 0x1a000, v8
	s_nop 1
	v_addc_co_u32_e32 v5, vcc, 0, v9, vcc
	global_store_dword v[4:5], v6, off offset:192
.LBB0_770:
	s_or_b64 exec, exec, s[10:11]
	v_rcp_f32_e32 v4, v7
	s_waitcnt lgkmcnt(0)
	v_mul_f32_e32 v5, v81, v4
	s_nop 1
	v_mov_b32_dpp v6, v5 quad_perm:[1,0,3,2] row_mask:0xf bank_mask:0xf
	s_and_saveexec_b64 s[10:11], s[6:7]
	s_cbranch_execz .LBB0_772
	v_lshl_add_u64 v[8:9], s[8:9], 0, v[2:3]
	s_waitcnt lgkmcnt(0)
	v_cvt_pk_bf16_f32 v5, v5, v6
	v_add_co_u32_e32 v6, vcc, 0x1b000, v8
	s_nop 1
	v_addc_co_u32_e32 v7, vcc, 0, v9, vcc
	global_store_dword v[6:7], v5, off
.LBB0_772:
	s_or_b64 exec, exec, s[10:11]
	v_mul_f32_e32 v5, v65, v4
	s_waitcnt lgkmcnt(0)
	s_nop 1
	v_mov_b32_dpp v6, v5 quad_perm:[1,0,3,2] row_mask:0xf bank_mask:0xf
	s_and_saveexec_b64 s[10:11], s[6:7]
	s_cbranch_execz .LBB0_774
	v_lshl_add_u64 v[8:9], s[8:9], 0, v[2:3]
	s_waitcnt lgkmcnt(0)
	v_cvt_pk_bf16_f32 v5, v5, v6
	v_add_co_u32_e32 v6, vcc, 0x1b000, v8
	s_nop 1
	v_addc_co_u32_e32 v7, vcc, 0, v9, vcc
	global_store_dword v[6:7], v5, off offset:64
.LBB0_774:
	s_or_b64 exec, exec, s[10:11]
	v_mul_f32_e32 v5, v49, v4
	s_waitcnt lgkmcnt(0)
	s_nop 1
	v_mov_b32_dpp v6, v5 quad_perm:[1,0,3,2] row_mask:0xf bank_mask:0xf
	s_and_saveexec_b64 s[10:11], s[6:7]
	s_cbranch_execz .LBB0_776
	v_lshl_add_u64 v[8:9], s[8:9], 0, v[2:3]
	s_waitcnt lgkmcnt(0)
	v_cvt_pk_bf16_f32 v5, v5, v6
	v_add_co_u32_e32 v6, vcc, 0x1b000, v8
	s_nop 1
	v_addc_co_u32_e32 v7, vcc, 0, v9, vcc
	global_store_dword v[6:7], v5, off offset:128
.LBB0_776:
	s_or_b64 exec, exec, s[10:11]
	v_mul_f32_e32 v4, v33, v4
	s_nop 1
	v_mov_b32_dpp v5, v4 quad_perm:[1,0,3,2] row_mask:0xf bank_mask:0xf
	s_and_saveexec_b64 s[10:11], s[6:7]
	s_cbranch_execz .LBB0_778
	s_waitcnt lgkmcnt(1)
	v_lshl_add_u64 v[6:7], s[8:9], 0, v[2:3]
	s_waitcnt lgkmcnt(0)
	v_cvt_pk_bf16_f32 v2, v4, v5
	v_add_co_u32_e32 v4, vcc, 0x1b000, v6
	s_nop 1
	v_addc_co_u32_e32 v5, vcc, 0, v7, vcc
	global_store_dword v[4:5], v2, off offset:192
